# v30 + diff pass-2 epilogue row reductions by DPP adds and v_permlane16_swap instead of ds_bpermute round trips
# speedup vs baseline: 1.0092x; 1.0043x over previous
; __device__ __forceinline__ int crow(int r, int hi) { return (r & 3) + 8 * (r >> 2) + 4 * hi; }
; __device__ __forceinline__ float xhalf_sum(float m) { auto rr = __builtin_amdgcn_permlane32_swap(__float_as_uint(m), __float_as_uint(m), false, false); return __uint_as_float(rr[0]) + __uint_as_float(rr[1]); }
; template <int DQK>
; __device__ __forceinline__ void attn_pass4(LAS unsigned char* lds, const bf16* Qp, int qpitch, const bf16* Kp, int kpitch, const bf16* Vp, int vpitch, int q0, f32x16 (&o)[4], float (&rl)[16]) {
;     ...
;     l = xhalf_sum(l);
;     if (hi == 0) wsf[32 + r32] = l;
;     asm volatile("s_waitcnt lgkmcnt(0)" ::: "memory");
; #pragma unroll
;     for (int r = 0; r < 16; ++r) rl[r] = 1.0f / wsf[32 + crow(r, hi)];
; __global__ void __launch_bounds__(NWAVES * 64, 2) fwd_kernel(Args args) {
;     ...
;                 for (int r = 0; r < 16; ++r) {
;                     float v[4], sq = 0.f;
; #pragma unroll
;                     for (int db = 0; db < 4; ++db) { v[db] = ((const float*)scrO)[db * 16 + r] - lam * o[db][r] * rl[r]; sq += v[db] * v[db]; }
.LBB0_608:
	s_waitcnt lgkmcnt(3)
	v_div_scale_f32 v32, s[2:3], v110, v110, 1.0
	v_rcp_f32_e32 v114, v32
	s_waitcnt lgkmcnt(0)
	s_barrier
	v_fma_f32 v115, -v32, v114, 1.0
	v_fmac_f32_e32 v114, v115, v114
	v_div_scale_f32 v115, vcc, 1.0, v110, 1.0
	v_mul_f32_e32 v116, v115, v114
	v_fma_f32 v117, -v32, v116, v115
	v_fmac_f32_e32 v116, v117, v114
	v_fma_f32 v32, -v32, v116, v115
	v_div_fmas_f32 v32, v32, v114, v116
	v_div_fixup_f32 v198, v32, v110, 1.0
	v_div_scale_f32 v32, s[2:3], v111, v111, 1.0
	v_rcp_f32_e32 v110, v32
	v_mov_b32_e32 v216, v50
	v_mov_b32_e32 v217, v34
	v_mov_b32_e32 v34, v51
	v_fma_f32 v114, -v32, v110, 1.0
	v_fmac_f32_e32 v110, v114, v110
	v_div_scale_f32 v114, vcc, 1.0, v111, 1.0
	v_mul_f32_e32 v115, v114, v110
	v_fma_f32 v116, -v32, v115, v114
	v_fmac_f32_e32 v115, v116, v110
	v_fma_f32 v32, -v32, v115, v114
	v_div_fmas_f32 v32, v32, v110, v115
	v_div_fixup_f32 v200, v32, v111, 1.0
	v_div_scale_f32 v32, s[2:3], v112, v112, 1.0
	v_rcp_f32_e32 v110, v32
	v_pk_mul_f32 v[216:217], v[164:165], v[216:217]
	v_pk_mul_f32 v[34:35], v[164:165], v[34:35]
	s_mov_b64 s[14:15], 0
	v_fma_f32 v111, -v32, v110, 1.0
	v_fmac_f32_e32 v110, v111, v110
	v_div_scale_f32 v111, vcc, 1.0, v112, 1.0
	v_mul_f32_e32 v114, v111, v110
	v_fma_f32 v115, -v32, v114, v111
	v_fmac_f32_e32 v114, v115, v110
	v_fma_f32 v32, -v32, v114, v111
	v_div_fmas_f32 v32, v32, v110, v114
	v_div_fixup_f32 v194, v32, v112, 1.0
	v_div_scale_f32 v32, s[2:3], v113, v113, 1.0
	v_rcp_f32_e32 v110, v32
	s_nop 0
	v_fma_f32 v111, -v32, v110, 1.0
	v_fmac_f32_e32 v110, v111, v110
	v_div_scale_f32 v111, vcc, 1.0, v113, 1.0
	v_mul_f32_e32 v112, v111, v110
	v_fma_f32 v114, -v32, v112, v111
	v_fmac_f32_e32 v112, v114, v110
	v_fma_f32 v32, -v32, v112, v111
	v_div_fmas_f32 v32, v32, v110, v112
	v_div_fixup_f32 v196, v32, v113, 1.0
	v_div_scale_f32 v32, s[2:3], v106, v106, 1.0
	v_rcp_f32_e32 v110, v32
	s_nop 0
	v_fma_f32 v111, -v32, v110, 1.0
	v_fmac_f32_e32 v110, v111, v110
	v_div_scale_f32 v111, vcc, 1.0, v106, 1.0
	v_mul_f32_e32 v112, v111, v110
	v_fma_f32 v113, -v32, v112, v111
	v_fmac_f32_e32 v112, v113, v110
	v_fma_f32 v32, -v32, v112, v111
	v_div_fmas_f32 v32, v32, v110, v112
	v_div_fixup_f32 v190, v32, v106, 1.0
	v_div_scale_f32 v32, s[2:3], v107, v107, 1.0
	v_rcp_f32_e32 v106, v32
	s_nop 0
	v_fma_f32 v110, -v32, v106, 1.0
	v_fmac_f32_e32 v106, v110, v106
	v_div_scale_f32 v110, vcc, 1.0, v107, 1.0
	v_mul_f32_e32 v111, v110, v106
	v_fma_f32 v112, -v32, v111, v110
	v_fmac_f32_e32 v111, v112, v106
	v_fma_f32 v32, -v32, v111, v110
	v_div_fmas_f32 v32, v32, v106, v111
	v_div_fixup_f32 v192, v32, v107, 1.0
	v_div_scale_f32 v32, s[2:3], v108, v108, 1.0
	v_rcp_f32_e32 v106, v32
	s_nop 0
	v_fma_f32 v107, -v32, v106, 1.0
	v_fmac_f32_e32 v106, v107, v106
	v_div_scale_f32 v107, vcc, 1.0, v108, 1.0
	v_mul_f32_e32 v110, v107, v106
	v_fma_f32 v111, -v32, v110, v107
	v_fmac_f32_e32 v110, v111, v106
	v_fma_f32 v32, -v32, v110, v107
	v_div_fmas_f32 v32, v32, v106, v110
	v_div_fixup_f32 v186, v32, v108, 1.0
	v_div_scale_f32 v32, s[2:3], v109, v109, 1.0
	v_rcp_f32_e32 v106, v32
	s_nop 0
	v_fma_f32 v107, -v32, v106, 1.0
	v_fmac_f32_e32 v106, v107, v106
	v_div_scale_f32 v107, vcc, 1.0, v109, 1.0
	v_mul_f32_e32 v108, v107, v106
	v_fma_f32 v110, -v32, v108, v107
	v_fmac_f32_e32 v108, v110, v106
	v_fma_f32 v32, -v32, v108, v107
	v_div_fmas_f32 v32, v32, v106, v108
	v_div_fixup_f32 v188, v32, v109, 1.0
	v_div_scale_f32 v32, s[2:3], v102, v102, 1.0
	v_rcp_f32_e32 v106, v32
	s_nop 0
	v_fma_f32 v107, -v32, v106, 1.0
	v_fmac_f32_e32 v106, v107, v106
	v_div_scale_f32 v107, vcc, 1.0, v102, 1.0
	v_mul_f32_e32 v108, v107, v106
	v_fma_f32 v109, -v32, v108, v107
	v_fmac_f32_e32 v108, v109, v106
	v_fma_f32 v32, -v32, v108, v107
	v_div_fmas_f32 v32, v32, v106, v108
	v_div_fixup_f32 v182, v32, v102, 1.0
	v_div_scale_f32 v32, s[2:3], v103, v103, 1.0
	v_rcp_f32_e32 v102, v32
	s_nop 0
	v_fma_f32 v106, -v32, v102, 1.0
	v_fmac_f32_e32 v102, v106, v102
	v_div_scale_f32 v106, vcc, 1.0, v103, 1.0
	v_mul_f32_e32 v107, v106, v102
	v_fma_f32 v108, -v32, v107, v106
	v_fmac_f32_e32 v107, v108, v102
	v_fma_f32 v32, -v32, v107, v106
	v_div_fmas_f32 v32, v32, v102, v107
	v_div_fixup_f32 v184, v32, v103, 1.0
	v_div_scale_f32 v32, s[2:3], v104, v104, 1.0
	v_rcp_f32_e32 v102, v32
	s_nop 0
	v_fma_f32 v103, -v32, v102, 1.0
	v_fmac_f32_e32 v102, v103, v102
	v_div_scale_f32 v103, vcc, 1.0, v104, 1.0
	v_mul_f32_e32 v106, v103, v102
	v_fma_f32 v107, -v32, v106, v103
	v_fmac_f32_e32 v106, v107, v102
	v_fma_f32 v32, -v32, v106, v103
	v_div_fmas_f32 v32, v32, v102, v106
	v_div_fixup_f32 v180, v32, v104, 1.0
	v_div_scale_f32 v32, s[2:3], v105, v105, 1.0
	v_rcp_f32_e32 v102, v32
	v_mov_b32_e32 v107, v66
	v_mov_b32_e32 v66, v83
	v_pk_mul_f32 v[66:67], v[164:165], v[66:67]
	v_fma_f32 v103, -v32, v102, 1.0
	v_fmac_f32_e32 v102, v103, v102
	v_div_scale_f32 v103, vcc, 1.0, v105, 1.0
	v_mul_f32_e32 v104, v103, v102
	v_fma_f32 v106, -v32, v104, v103
	v_fmac_f32_e32 v104, v106, v102
	v_fma_f32 v32, -v32, v104, v103
	v_div_fmas_f32 v32, v32, v102, v104
	v_div_fixup_f32 v178, v32, v105, 1.0
	v_div_scale_f32 v32, s[2:3], v98, v98, 1.0
	v_rcp_f32_e32 v102, v32
	v_mov_b32_e32 v106, v82
	v_pk_mul_f32 v[106:107], v[164:165], v[106:107]
	v_fma_f32 v103, -v32, v102, 1.0
	v_fmac_f32_e32 v102, v103, v102
	v_div_scale_f32 v103, vcc, 1.0, v98, 1.0
	v_mul_f32_e32 v104, v103, v102
	v_fma_f32 v105, -v32, v104, v103
	v_fmac_f32_e32 v104, v105, v102
	v_fma_f32 v32, -v32, v104, v103
	v_div_fmas_f32 v32, v32, v102, v104
	v_div_fixup_f32 v176, v32, v98, 1.0
	v_div_scale_f32 v32, s[2:3], v99, v99, 1.0
	v_rcp_f32_e32 v98, v32
	s_nop 0
	v_fma_f32 v102, -v32, v98, 1.0
; __global__ void __launch_bounds__(NWAVES * 64, 2) fwd_kernel(Args args) {
;     ...
;                 int t2 = threadIdx.x; asm volatile("" : "+v"(t2));
;                 const int r32 = t2 & 31, hi = (t2 >> 5) & 1; const size_t row0 = (size_t)b * SEQ + qb * 256 + (t2 >> 6) * 32;
;                 scrO = (f32x4*)((float*)(ws + WS_O0) + ((size_t)bx * 512 + t2) * 64);
;                 float g4[4];
; #pragma unroll
;                 for (int db = 0; db < 4; ++db) g4[db] = args.sub_gain[32 * db + r32] * post;
; #pragma unroll
;                 for (int r = 0; r < 16; ++r) {
;                     float v[4], sq = 0.f;
; #pragma unroll
;                     for (int db = 0; db < 4; ++db) { v[db] = ((const float*)scrO)[db * 16 + r] - lam * o[db][r] * rl[r]; sq += v[db] * v[db]; }
	v_fmac_f32_e32 v98, v102, v98
	v_div_scale_f32 v102, vcc, 1.0, v99, 1.0
	v_mul_f32_e32 v103, v102, v98
	v_fma_f32 v104, -v32, v103, v102
	v_fmac_f32_e32 v103, v104, v98
	v_fma_f32 v32, -v32, v103, v102
	v_div_fmas_f32 v32, v32, v98, v103
	v_div_fixup_f32 v174, v32, v99, 1.0
	v_div_scale_f32 v32, s[2:3], v100, v100, 1.0
	v_rcp_f32_e32 v98, v32
	s_nop 0
	v_fma_f32 v99, -v32, v98, 1.0
	v_fmac_f32_e32 v98, v99, v98
	v_div_scale_f32 v99, vcc, 1.0, v100, 1.0
	v_mul_f32_e32 v102, v99, v98
	v_fma_f32 v103, -v32, v102, v99
	v_fmac_f32_e32 v102, v103, v98
	v_fma_f32 v32, -v32, v102, v99
	v_div_fmas_f32 v32, v32, v98, v102
	v_div_fixup_f32 v168, v32, v100, 1.0
	v_div_scale_f32 v32, s[2:3], v101, v101, 1.0
	v_rcp_f32_e32 v98, v32
	s_or_b32 s2, s48, s30
	s_mov_b32 s3, s49
	v_fma_f32 v99, -v32, v98, 1.0
	v_fmac_f32_e32 v98, v99, v98
	v_div_scale_f32 v99, vcc, 1.0, v101, 1.0
	v_mul_f32_e32 v100, v99, v98
	v_fma_f32 v102, -v32, v100, v99
	v_fmac_f32_e32 v100, v102, v98
	v_fma_f32 v32, -v32, v100, v99
	v_div_fmas_f32 v32, v32, v98, v100
	v_mov_b32_e32 v98, v242
	v_div_fixup_f32 v166, v32, v101, 1.0
	v_ashrrev_i32_e32 v99, 1, v98
	v_and_b32_e32 v32, 31, v98
	v_and_b32_e32 v100, 0xffffffe0, v99
	v_ashrrev_i32_e32 v99, 31, v98
	v_lshl_add_u64 v[102:103], s[42:43], 0, v[98:99]
	v_lshlrev_b32_e32 v99, 2, v32
	global_load_dword v104, v99, s[44:45]
	v_ashrrev_i32_e32 v101, 31, v100
	v_lshl_add_u64 v[170:171], s[2:3], 0, v[100:101]
	v_and_b32_e32 v100, 64, v209
	v_add_u32_e32 v100, 64, v100
	v_lshlrev_b64 v[102:103], 8, v[102:103]
	s_waitcnt vmcnt(1)
	v_lshl_add_u64 v[158:159], s[28:29], 0, v[102:103]
	v_lshrrev_b32_e32 v214, 3, v98
	s_mov_b32 s2, 0x358637bd
	v_lshlrev_b32_e32 v32, 1, v32
	v_lshl_add_u64 v[172:173], s[58:59], 0, v[32:33]
	v_and_or_b32 v170, v214, 4, v170
	v_lshlrev_b64 v[214:215], 11, v[170:171]
	v_lshl_add_u64 v[214:215], v[172:173], 0, v[214:215]
	s_waitcnt vmcnt(0)
	v_mul_f32_e32 v167, 0x3f4ccccd, v104
	global_load_dword v104, v99, s[44:45] offset:128
	s_waitcnt vmcnt(0)
	v_mul_f32_e32 v169, 0x3f4ccccd, v104
	global_load_dword v104, v99, s[44:45] offset:256
	s_waitcnt vmcnt(0)
	v_mul_f32_e32 v175, 0x3f4ccccd, v104
	global_load_dword v99, v99, s[44:45] offset:384
	s_waitcnt vmcnt(0)
	v_mul_f32_e32 v177, 0x3f4ccccd, v99
	v_xor_b32_e32 v99, 1, v209
	v_cmp_lt_i32_e32 vcc, v99, v100
	s_nop 1
	v_cndmask_b32_e32 v99, v209, v99, vcc
	v_lshlrev_b32_e32 v213, 2, v99
	v_xor_b32_e32 v99, 2, v209
	v_cmp_lt_i32_e32 vcc, v99, v100
	s_nop 1
	v_cndmask_b32_e32 v99, v209, v99, vcc
	v_lshlrev_b32_e32 v212, 2, v99
	v_xor_b32_e32 v99, 4, v209
	v_cmp_lt_i32_e32 vcc, v99, v100
	s_nop 1
	v_cndmask_b32_e32 v99, v209, v99, vcc
	v_lshlrev_b32_e32 v211, 2, v99
	v_xor_b32_e32 v99, 8, v209
	v_cmp_lt_i32_e32 vcc, v99, v100
	s_nop 1
	v_cndmask_b32_e32 v99, v209, v99, vcc
	v_lshlrev_b32_e32 v210, 2, v99
	v_xor_b32_e32 v99, 16, v209
	v_cmp_lt_i32_e32 vcc, v99, v100
	s_nop 1
	v_cndmask_b32_e32 v99, v209, v99, vcc
	v_lshlrev_b32_e32 v179, 2, v99
	global_load_dwordx4 v[98:101], v[158:159], off offset:48
	global_load_dwordx4 v[114:117], v[158:159], off offset:32
	global_load_dwordx4 v[130:133], v[158:159], off offset:16
	global_load_dwordx4 v[146:149], v[158:159], off
	global_load_dwordx4 v[102:105], v[158:159], off offset:112
	global_load_dwordx4 v[118:121], v[158:159], off offset:96
	global_load_dwordx4 v[134:137], v[158:159], off offset:80
	global_load_dwordx4 v[150:153], v[158:159], off offset:64
	s_waitcnt vmcnt(4)
	v_mov_b32_e32 v108, v146
	s_waitcnt vmcnt(0)
	v_mov_b32_e32 v109, v150
	v_pk_fma_f32 v[202:203], v[198:199], v[106:107], v[108:109] op_sel_hi:[0,1,1] neg_lo:[1,0,0] neg_hi:[1,0,0]
	global_load_dwordx4 v[106:109], v[158:159], off offset:176
	global_load_dwordx4 v[122:125], v[158:159], off offset:160
	global_load_dwordx4 v[138:141], v[158:159], off offset:144
	global_load_dwordx4 v[154:157], v[158:159], off offset:128
	global_load_dwordx4 v[110:113], v[158:159], off offset:240
	global_load_dwordx4 v[126:129], v[158:159], off offset:224
	global_load_dwordx4 v[142:145], v[158:159], off offset:208
	s_nop 0
	global_load_dwordx4 v[158:161], v[158:159], off offset:192
	v_mov_b32_e32 v150, v147
	v_pk_fma_f32 v[66:67], v[200:201], v[66:67], v[150:151] op_sel_hi:[0,1,1] neg_lo:[1,0,0] neg_hi:[1,0,0]
	v_pk_mul_f32 v[204:205], v[202:203], v[202:203]
	v_pk_mul_f32 v[82:83], v[66:67], v[66:67]
	v_mov_b32_e32 v147, v204
	v_mov_b32_e32 v146, v82
	v_mov_b32_e32 v204, v83
	v_pk_add_f32 v[82:83], v[146:147], v[204:205]
	v_or_b32_e32 v150, 2, v170
	v_mov_b32_e32 v151, v171
	v_lshlrev_b64 v[150:151], 11, v[150:151]
	v_lshl_add_u64 v[150:151], v[172:173], 0, v[150:151]
	s_waitcnt vmcnt(4)
	v_mov_b32_e32 v218, v154
	s_waitcnt vmcnt(0)
; __device__ __forceinline__ unsigned f2bf(float f) { unsigned u = __builtin_bit_cast(unsigned, f); return (u + 0x7fffu + ((u >> 16) & 1u)) >> 16; }
; __device__ __forceinline__ int crow(int r, int hi) { return (r & 3) + 8 * (r >> 2) + 4 * hi; }
; __global__ void __launch_bounds__(NWAVES * 64, 2) fwd_kernel(Args args) {
;     ...
;                 for (int r = 0; r < 16; ++r) {
;                     float v[4], sq = 0.f;
; #pragma unroll
;                     for (int db = 0; db < 4; ++db) { v[db] = ((const float*)scrO)[db * 16 + r] - lam * o[db][r] * rl[r]; sq += v[db] * v[db]; }
;                     sq += __shfl_xor(sq, 1); sq += __shfl_xor(sq, 2); sq += __shfl_xor(sq, 4); sq += __shfl_xor(sq, 8); sq += __shfl_xor(sq, 16);
;                     const float rs = rsqrtf(sq * (1.0f / 128.0f) + 1e-6f);
;                     bf16* orow = AO + (row0 + att::crow(r, hi)) * 1024 + h * 128 + r32;
; #pragma unroll
;                     for (int db = 0; db < 4; ++db) orow[32 * db] = (bf16)f2bf(v[db] * rs * g4[db]);
	v_mov_b32_e32 v219, v158
	v_mov_b32_e32 v158, v155
	v_pk_fma_f32 v[216:217], v[198:199], v[216:217], v[218:219] op_sel_hi:[0,1,1] neg_lo:[1,0,0] neg_hi:[1,0,0]
	v_pk_fma_f32 v[50:51], v[200:201], v[34:35], v[158:159] op_sel_hi:[0,1,1] neg_lo:[1,0,0] neg_hi:[1,0,0]
	v_pk_mul_f32 v[218:219], v[216:217], v[216:217]
	v_pk_mul_f32 v[34:35], v[50:51], v[50:51]
	v_mov_b32_e32 v147, v218
	v_mov_b32_e32 v146, v34
	v_pk_add_f32 v[82:83], v[82:83], v[146:147]
	v_mov_b32_e32 v218, v35
	v_pk_add_f32 v[34:35], v[82:83], v[218:219]
	s_nop 1
	v_add_f32_dpp v34, v34, v34 quad_perm:[1,0,3,2] row_mask:0xf bank_mask:0xf
	v_add_f32_dpp v35, v35, v35 quad_perm:[1,0,3,2] row_mask:0xf bank_mask:0xf
	s_nop 0
	v_add_f32_dpp v34, v34, v34 quad_perm:[2,3,0,1] row_mask:0xf bank_mask:0xf
	v_add_f32_dpp v35, v35, v35 quad_perm:[2,3,0,1] row_mask:0xf bank_mask:0xf
	s_nop 0
	v_add_f32_dpp v34, v34, v34 row_half_mirror row_mask:0xf bank_mask:0xf
	v_add_f32_dpp v35, v35, v35 row_half_mirror row_mask:0xf bank_mask:0xf
	s_nop 0
	v_add_f32_dpp v34, v34, v34 row_mirror row_mask:0xf bank_mask:0xf
	v_add_f32_dpp v35, v35, v35 row_mirror row_mask:0xf bank_mask:0xf
	s_nop 0
	v_mov_b32_e32 v82, v34
	v_mov_b32_e32 v83, v35
	s_nop 0
	v_permlane16_swap_b32_e32 v34, v82
	v_permlane16_swap_b32_e32 v35, v83
	v_add_f32_e32 v82, v34, v82
	v_add_f32_e32 v83, v35, v83
	v_mov_b32_e32 v147, v160
	v_mov_b32_e32 v160, v157
	v_mov_b64_e32 v[34:35], s[2:3]
	v_pk_fma_f32 v[82:83], v[82:83], s[46:47], v[34:35] op_sel_hi:[1,0,0]
	s_nop 0
	v_mul_f32_e32 v32, 0x4b800000, v83
	v_cmp_gt_f32_e64 s[8:9], s34, v83
	v_cmp_gt_f32_e32 vcc, s34, v82
	s_nop 0
	v_cndmask_b32_e64 v32, v83, v32, s[8:9]
	v_rsq_f32_e32 v32, v32
	s_nop 0
	v_mul_f32_e32 v83, 0x45800000, v32
	v_cndmask_b32_e64 v32, v32, v83, s[8:9]
	v_mul_f32_e32 v83, v32, v202
	v_mul_f32_e32 v83, v83, v167
	v_bfe_u32 v146, v83, 16, 1
	v_add3_u32 v83, v83, v146, s40
	global_store_short_d16_hi v[214:215], v83, off
	v_mul_f32_e32 v83, v32, v203
	v_mul_f32_e32 v83, v83, v169
	v_bfe_u32 v146, v83, 16, 1
	v_add3_u32 v83, v83, v146, s40
	global_store_short_d16_hi v[214:215], v83, off offset:64
	v_mul_f32_e32 v83, v32, v216
	v_mul_f32_e32 v83, v83, v175
	v_bfe_u32 v146, v83, 16, 1
	v_mul_f32_e32 v32, v32, v217
	v_add3_u32 v83, v83, v146, s40
	v_mul_f32_e32 v32, v32, v177
	global_store_short_d16_hi v[214:215], v83, off offset:128
	v_bfe_u32 v83, v32, 16, 1
	v_add3_u32 v32, v32, v83, s40
	global_store_short_d16_hi v[214:215], v32, off offset:192
	v_mul_f32_e32 v32, 0x4b800000, v82
	v_cndmask_b32_e32 v32, v82, v32, vcc
	v_rsq_f32_e32 v32, v32
	v_mov_b32_e32 v83, v171
	v_mul_f32_e32 v82, 0x45800000, v32
	v_cndmask_b32_e32 v32, v32, v82, vcc
	v_mul_f32_e32 v66, v32, v66
	v_or_b32_e32 v82, 1, v170
	v_mul_f32_e32 v66, v66, v167
	v_lshlrev_b64 v[82:83], 11, v[82:83]
	v_bfe_u32 v146, v66, 16, 1
	v_lshl_add_u64 v[82:83], v[172:173], 0, v[82:83]
	v_add3_u32 v66, v66, v146, s40
	global_store_short_d16_hi v[82:83], v66, off
	v_mul_f32_e32 v66, v32, v67
	v_mul_f32_e32 v66, v66, v169
	v_bfe_u32 v67, v66, 16, 1
	v_mul_f32_e32 v50, v32, v50
	v_add3_u32 v66, v66, v67, s40
	v_mul_f32_e32 v50, v50, v175
	global_store_short_d16_hi v[82:83], v66, off offset:64
	v_bfe_u32 v66, v50, 16, 1
	v_mul_f32_e32 v32, v32, v51
	v_add3_u32 v50, v50, v66, s40
	v_mul_f32_e32 v32, v32, v177
	global_store_short_d16_hi v[82:83], v50, off offset:128
	v_bfe_u32 v50, v32, 16, 1
	v_add3_u32 v32, v32, v50, s40
	v_mov_b32_e32 v50, v84
	v_mov_b32_e32 v51, v68
	v_mov_b32_e32 v68, v85
	global_store_short_d16_hi v[82:83], v32, off offset:192
	v_pk_mul_f32 v[50:51], v[164:165], v[50:51]
	v_mov_b32_e32 v66, v148
	v_mov_b32_e32 v67, v152
	v_mov_b32_e32 v82, v52
	v_mov_b32_e32 v83, v36
	v_pk_mul_f32 v[68:69], v[164:165], v[68:69]
	v_mov_b32_e32 v152, v149
	v_mov_b32_e32 v36, v53
	v_pk_fma_f32 v[50:51], v[194:195], v[50:51], v[66:67] op_sel_hi:[0,1,1] neg_lo:[1,0,0] neg_hi:[1,0,0]
	v_pk_mul_f32 v[82:83], v[164:165], v[82:83]
	v_mov_b32_e32 v146, v156
	v_pk_fma_f32 v[68:69], v[196:197], v[68:69], v[152:153] op_sel_hi:[0,1,1] neg_lo:[1,0,0] neg_hi:[1,0,0]
	v_pk_mul_f32 v[36:37], v[164:165], v[36:37]
	v_pk_mul_f32 v[66:67], v[50:51], v[50:51]
	v_pk_fma_f32 v[82:83], v[194:195], v[82:83], v[146:147] op_sel_hi:[0,1,1] neg_lo:[1,0,0] neg_hi:[1,0,0]
	v_pk_mul_f32 v[84:85], v[68:69], v[68:69]
	v_pk_fma_f32 v[36:37], v[196:197], v[36:37], v[160:161] op_sel_hi:[0,1,1] neg_lo:[1,0,0] neg_hi:[1,0,0]
	v_pk_mul_f32 v[146:147], v[82:83], v[82:83]
	v_pk_mul_f32 v[52:53], v[36:37], v[36:37]
	v_mov_b32_e32 v148, v84
	v_mov_b32_e32 v149, v66
	v_mov_b32_e32 v66, v85
	v_pk_add_f32 v[66:67], v[148:149], v[66:67]
	v_mov_b32_e32 v84, v52
	v_mov_b32_e32 v85, v146
	v_pk_add_f32 v[66:67], v[66:67], v[84:85]
	v_mov_b32_e32 v146, v53
	v_pk_add_f32 v[52:53], v[66:67], v[146:147]
	s_nop 1
	v_add_f32_dpp v52, v52, v52 quad_perm:[1,0,3,2] row_mask:0xf bank_mask:0xf
	v_add_f32_dpp v53, v53, v53 quad_perm:[1,0,3,2] row_mask:0xf bank_mask:0xf
	s_nop 0
	v_add_f32_dpp v52, v52, v52 quad_perm:[2,3,0,1] row_mask:0xf bank_mask:0xf
	v_add_f32_dpp v53, v53, v53 quad_perm:[2,3,0,1] row_mask:0xf bank_mask:0xf
	s_nop 0
	v_add_f32_dpp v52, v52, v52 row_half_mirror row_mask:0xf bank_mask:0xf
	v_add_f32_dpp v53, v53, v53 row_half_mirror row_mask:0xf bank_mask:0xf
	s_nop 0
	v_add_f32_dpp v52, v52, v52 row_mirror row_mask:0xf bank_mask:0xf
	v_add_f32_dpp v53, v53, v53 row_mirror row_mask:0xf bank_mask:0xf
	s_nop 0
	v_mov_b32_e32 v66, v52
	v_mov_b32_e32 v67, v53
	s_nop 0
	v_permlane16_swap_b32_e32 v52, v66
	v_permlane16_swap_b32_e32 v53, v67
	v_add_f32_e32 v52, v52, v66
	v_add_f32_e32 v53, v53, v67
	s_nop 0
	v_pk_fma_f32 v[52:53], v[52:53], s[46:47], v[34:35] op_sel_hi:[1,0,0]
; __device__ __forceinline__ unsigned f2bf(float f) { unsigned u = __builtin_bit_cast(unsigned, f); return (u + 0x7fffu + ((u >> 16) & 1u)) >> 16; }
; __device__ __forceinline__ int crow(int r, int hi) { return (r & 3) + 8 * (r >> 2) + 4 * hi; }
; __global__ void __launch_bounds__(NWAVES * 64, 2) fwd_kernel(Args args) {
;     ...
;                 for (int r = 0; r < 16; ++r) {
;                     float v[4], sq = 0.f;
; #pragma unroll
;                     for (int db = 0; db < 4; ++db) { v[db] = ((const float*)scrO)[db * 16 + r] - lam * o[db][r] * rl[r]; sq += v[db] * v[db]; }
;                     sq += __shfl_xor(sq, 1); sq += __shfl_xor(sq, 2); sq += __shfl_xor(sq, 4); sq += __shfl_xor(sq, 8); sq += __shfl_xor(sq, 16);
;                     const float rs = rsqrtf(sq * (1.0f / 128.0f) + 1e-6f);
;                     bf16* orow = AO + (row0 + att::crow(r, hi)) * 1024 + h * 128 + r32;
; #pragma unroll
;                     for (int db = 0; db < 4; ++db) orow[32 * db] = (bf16)f2bf(v[db] * rs * g4[db]);
	v_mov_b32_e32 v66, v138
	v_mul_f32_e32 v32, 0x4b800000, v53
	v_cmp_gt_f32_e64 s[8:9], s34, v53
	v_cmp_gt_f32_e32 vcc, s34, v52
	v_mov_b32_e32 v67, v142
	v_cndmask_b32_e64 v32, v53, v32, s[8:9]
	v_rsq_f32_e32 v32, v32
	v_mov_b32_e32 v142, v139
	v_mul_f32_e32 v53, 0x45800000, v32
	v_cndmask_b32_e64 v32, v32, v53, s[8:9]
	v_mul_f32_e32 v50, v32, v50
	v_mul_f32_e32 v50, v50, v167
	v_bfe_u32 v53, v50, 16, 1
	v_add3_u32 v50, v50, v53, s40
	global_store_short_d16_hi v[150:151], v50, off
	v_mul_f32_e32 v50, v32, v51
	v_mul_f32_e32 v50, v50, v169
	v_bfe_u32 v51, v50, 16, 1
	v_add3_u32 v50, v50, v51, s40
	global_store_short_d16_hi v[150:151], v50, off offset:64
	v_mul_f32_e32 v50, v32, v82
	v_mul_f32_e32 v50, v50, v175
	v_bfe_u32 v51, v50, 16, 1
	v_mul_f32_e32 v32, v32, v83
	v_add3_u32 v50, v50, v51, s40
	v_mul_f32_e32 v32, v32, v177
	global_store_short_d16_hi v[150:151], v50, off offset:128
	v_bfe_u32 v50, v32, 16, 1
	v_add3_u32 v32, v32, v50, s40
	global_store_short_d16_hi v[150:151], v32, off offset:192
	v_mul_f32_e32 v32, 0x4b800000, v52
	v_cndmask_b32_e32 v32, v52, v32, vcc
	v_rsq_f32_e32 v32, v32
	v_mov_b32_e32 v51, v171
	v_mul_f32_e32 v50, 0x45800000, v32
	v_cndmask_b32_e32 v32, v32, v50, vcc
	v_mul_f32_e32 v52, v32, v68
	v_or_b32_e32 v50, 3, v170
	v_mul_f32_e32 v52, v52, v167
	v_lshlrev_b64 v[50:51], 11, v[50:51]
	v_bfe_u32 v53, v52, 16, 1
	v_lshl_add_u64 v[50:51], v[172:173], 0, v[50:51]
	v_add3_u32 v52, v52, v53, s40
	global_store_short_d16_hi v[50:51], v52, off
	v_mul_f32_e32 v52, v32, v69
	v_mul_f32_e32 v52, v52, v169
	v_bfe_u32 v53, v52, 16, 1
	v_mul_f32_e32 v36, v32, v36
	v_add3_u32 v52, v52, v53, s40
	v_mul_f32_e32 v36, v36, v175
	global_store_short_d16_hi v[50:51], v52, off offset:64
	v_bfe_u32 v52, v36, 16, 1
	v_mul_f32_e32 v32, v32, v37
	v_add3_u32 v36, v36, v52, s40
	v_mul_f32_e32 v32, v32, v177
	global_store_short_d16_hi v[50:51], v36, off offset:128
	v_bfe_u32 v36, v32, 16, 1
	v_add3_u32 v32, v32, v36, s40
	v_mov_b32_e32 v36, v86
	v_mov_b32_e32 v37, v70
	v_mov_b32_e32 v70, v87
	global_store_short_d16_hi v[50:51], v32, off offset:192
	v_pk_mul_f32 v[36:37], v[164:165], v[36:37]
	v_mov_b32_e32 v50, v130
	v_mov_b32_e32 v51, v134
	v_mov_b32_e32 v52, v54
	v_mov_b32_e32 v53, v38
	v_pk_mul_f32 v[70:71], v[164:165], v[70:71]
	v_mov_b32_e32 v134, v131
	v_mov_b32_e32 v38, v55
	v_pk_fma_f32 v[36:37], v[190:191], v[36:37], v[50:51] op_sel_hi:[0,1,1] neg_lo:[1,0,0] neg_hi:[1,0,0]
	v_pk_mul_f32 v[52:53], v[164:165], v[52:53]
	v_pk_fma_f32 v[70:71], v[192:193], v[70:71], v[134:135] op_sel_hi:[0,1,1] neg_lo:[1,0,0] neg_hi:[1,0,0]
	v_pk_mul_f32 v[38:39], v[164:165], v[38:39]
	v_pk_mul_f32 v[50:51], v[36:37], v[36:37]
	v_pk_fma_f32 v[52:53], v[190:191], v[52:53], v[66:67] op_sel_hi:[0,1,1] neg_lo:[1,0,0] neg_hi:[1,0,0]
	v_pk_mul_f32 v[82:83], v[70:71], v[70:71]
	v_pk_fma_f32 v[38:39], v[192:193], v[38:39], v[142:143] op_sel_hi:[0,1,1] neg_lo:[1,0,0] neg_hi:[1,0,0]
	v_pk_mul_f32 v[66:67], v[52:53], v[52:53]
	v_pk_mul_f32 v[54:55], v[38:39], v[38:39]
	v_mov_b32_e32 v84, v82
	v_mov_b32_e32 v85, v50
	v_mov_b32_e32 v50, v83
	v_pk_add_f32 v[50:51], v[84:85], v[50:51]
	v_mov_b32_e32 v82, v54
	v_mov_b32_e32 v83, v66
	v_pk_add_f32 v[50:51], v[50:51], v[82:83]
	v_mov_b32_e32 v66, v55
	v_pk_add_f32 v[50:51], v[50:51], v[66:67]
	s_nop 1
	v_add_f32_dpp v50, v50, v50 quad_perm:[1,0,3,2] row_mask:0xf bank_mask:0xf
	v_add_f32_dpp v51, v51, v51 quad_perm:[1,0,3,2] row_mask:0xf bank_mask:0xf
	s_nop 0
	v_add_f32_dpp v50, v50, v50 quad_perm:[2,3,0,1] row_mask:0xf bank_mask:0xf
	v_add_f32_dpp v51, v51, v51 quad_perm:[2,3,0,1] row_mask:0xf bank_mask:0xf
	s_nop 0
	v_add_f32_dpp v50, v50, v50 row_half_mirror row_mask:0xf bank_mask:0xf
	v_add_f32_dpp v51, v51, v51 row_half_mirror row_mask:0xf bank_mask:0xf
	s_nop 0
	v_add_f32_dpp v50, v50, v50 row_mirror row_mask:0xf bank_mask:0xf
	v_add_f32_dpp v51, v51, v51 row_mirror row_mask:0xf bank_mask:0xf
	s_nop 0
	v_mov_b32_e32 v54, v50
	v_mov_b32_e32 v55, v51
	s_nop 0
	v_permlane16_swap_b32_e32 v50, v54
	v_permlane16_swap_b32_e32 v51, v55
	v_add_f32_e32 v50, v50, v54
	v_add_f32_e32 v51, v51, v55
	v_or_b32_e32 v68, 8, v170
	v_mov_b32_e32 v69, v171
	v_lshlrev_b64 v[68:69], 11, v[68:69]
	v_lshl_add_u64 v[68:69], v[172:173], 0, v[68:69]
	s_nop 0
	v_pk_fma_f32 v[50:51], v[50:51], s[46:47], v[34:35] op_sel_hi:[1,0,0]
	v_or_b32_e32 v54, 10, v170
	v_mul_f32_e32 v32, 0x4b800000, v51
	v_cmp_gt_f32_e64 s[8:9], s34, v51
	v_cmp_gt_f32_e32 vcc, s34, v50
	v_mov_b32_e32 v55, v171
	v_cndmask_b32_e64 v32, v51, v32, s[8:9]
	v_rsq_f32_e32 v32, v32
	v_lshlrev_b64 v[54:55], 11, v[54:55]
	v_lshl_add_u64 v[54:55], v[172:173], 0, v[54:55]
	v_mul_f32_e32 v51, 0x45800000, v32
	v_cndmask_b32_e64 v32, v32, v51, s[8:9]
	v_mul_f32_e32 v36, v32, v36
	v_mul_f32_e32 v36, v36, v167
	v_bfe_u32 v51, v36, 16, 1
	v_add3_u32 v36, v36, v51, s40
	global_store_short_d16_hi v[68:69], v36, off
	v_mul_f32_e32 v36, v32, v37
	v_mul_f32_e32 v36, v36, v169
	v_bfe_u32 v37, v36, 16, 1
	v_add3_u32 v36, v36, v37, s40
	global_store_short_d16_hi v[68:69], v36, off offset:64
	v_mul_f32_e32 v36, v32, v52
	v_mul_f32_e32 v36, v36, v175
	v_bfe_u32 v37, v36, 16, 1
	v_mul_f32_e32 v32, v32, v53
	v_add3_u32 v36, v36, v37, s40
	v_mul_f32_e32 v32, v32, v177
	global_store_short_d16_hi v[68:69], v36, off offset:128
	v_bfe_u32 v36, v32, 16, 1
	v_add3_u32 v32, v32, v36, s40
	global_store_short_d16_hi v[68:69], v32, off offset:192
	v_mul_f32_e32 v32, 0x4b800000, v50
	v_cndmask_b32_e32 v32, v50, v32, vcc
	v_rsq_f32_e32 v32, v32
	v_mov_b32_e32 v37, v171
	v_mov_b32_e32 v52, v140
	v_mov_b32_e32 v53, v144
	v_mul_f32_e32 v36, 0x45800000, v32
	v_cndmask_b32_e32 v32, v32, v36, vcc
	v_mul_f32_e32 v50, v32, v70
; __device__ __forceinline__ unsigned f2bf(float f) { unsigned u = __builtin_bit_cast(unsigned, f); return (u + 0x7fffu + ((u >> 16) & 1u)) >> 16; }
; __device__ __forceinline__ int crow(int r, int hi) { return (r & 3) + 8 * (r >> 2) + 4 * hi; }
; __global__ void __launch_bounds__(NWAVES * 64, 2) fwd_kernel(Args args) {
;     ...
;                 for (int r = 0; r < 16; ++r) {
;                     float v[4], sq = 0.f;
; #pragma unroll
;                     for (int db = 0; db < 4; ++db) { v[db] = ((const float*)scrO)[db * 16 + r] - lam * o[db][r] * rl[r]; sq += v[db] * v[db]; }
;                     sq += __shfl_xor(sq, 1); sq += __shfl_xor(sq, 2); sq += __shfl_xor(sq, 4); sq += __shfl_xor(sq, 8); sq += __shfl_xor(sq, 16);
;                     const float rs = rsqrtf(sq * (1.0f / 128.0f) + 1e-6f);
;                     bf16* orow = AO + (row0 + att::crow(r, hi)) * 1024 + h * 128 + r32;
; #pragma unroll
;                     for (int db = 0; db < 4; ++db) orow[32 * db] = (bf16)f2bf(v[db] * rs * g4[db]);
	v_or_b32_e32 v36, 9, v170
	v_mul_f32_e32 v50, v50, v167
	v_lshlrev_b64 v[36:37], 11, v[36:37]
	v_bfe_u32 v51, v50, 16, 1
	v_lshl_add_u64 v[36:37], v[172:173], 0, v[36:37]
	v_add3_u32 v50, v50, v51, s40
	global_store_short_d16_hi v[36:37], v50, off
	v_mul_f32_e32 v50, v32, v71
	v_mul_f32_e32 v50, v50, v169
	v_bfe_u32 v51, v50, 16, 1
	v_mul_f32_e32 v38, v32, v38
	v_add3_u32 v50, v50, v51, s40
	v_mul_f32_e32 v38, v38, v175
	global_store_short_d16_hi v[36:37], v50, off offset:64
	v_bfe_u32 v50, v38, 16, 1
	v_mul_f32_e32 v32, v32, v39
	v_add3_u32 v38, v38, v50, s40
	v_mul_f32_e32 v32, v32, v177
	global_store_short_d16_hi v[36:37], v38, off offset:128
	v_bfe_u32 v38, v32, 16, 1
	v_add3_u32 v32, v32, v38, s40
	global_store_short_d16_hi v[36:37], v32, off offset:192
	v_mov_b32_e32 v36, v88
	v_mov_b32_e32 v37, v72
	v_mov_b32_e32 v72, v89
	v_pk_mul_f32 v[36:37], v[164:165], v[36:37]
	v_mov_b32_e32 v38, v132
	v_mov_b32_e32 v39, v136
	v_mov_b32_e32 v50, v56
	v_mov_b32_e32 v51, v40
	v_pk_mul_f32 v[66:67], v[164:165], v[72:73]
	v_mov_b32_e32 v136, v133
	v_mov_b32_e32 v40, v57
	v_pk_fma_f32 v[36:37], v[186:187], v[36:37], v[38:39] op_sel_hi:[0,1,1] neg_lo:[1,0,0] neg_hi:[1,0,0]
	v_pk_mul_f32 v[50:51], v[164:165], v[50:51]
	v_pk_fma_f32 v[66:67], v[188:189], v[66:67], v[136:137] op_sel_hi:[0,1,1] neg_lo:[1,0,0] neg_hi:[1,0,0]
	v_pk_mul_f32 v[40:41], v[164:165], v[40:41]
	v_mov_b32_e32 v144, v141
	v_pk_mul_f32 v[38:39], v[36:37], v[36:37]
	v_pk_fma_f32 v[50:51], v[186:187], v[50:51], v[52:53] op_sel_hi:[0,1,1] neg_lo:[1,0,0] neg_hi:[1,0,0]
	v_pk_mul_f32 v[68:69], v[66:67], v[66:67]
	v_pk_fma_f32 v[40:41], v[188:189], v[40:41], v[144:145] op_sel_hi:[0,1,1] neg_lo:[1,0,0] neg_hi:[1,0,0]
	v_pk_mul_f32 v[52:53], v[50:51], v[50:51]
	v_pk_mul_f32 v[56:57], v[40:41], v[40:41]
	v_mov_b32_e32 v70, v68
	v_mov_b32_e32 v71, v38
	v_mov_b32_e32 v38, v69
	v_pk_add_f32 v[38:39], v[70:71], v[38:39]
	v_mov_b32_e32 v68, v56
	v_mov_b32_e32 v69, v52
	v_pk_add_f32 v[38:39], v[38:39], v[68:69]
	v_mov_b32_e32 v52, v57
	v_pk_add_f32 v[38:39], v[38:39], v[52:53]
	s_nop 1
	v_add_f32_dpp v38, v38, v38 quad_perm:[1,0,3,2] row_mask:0xf bank_mask:0xf
	v_add_f32_dpp v39, v39, v39 quad_perm:[1,0,3,2] row_mask:0xf bank_mask:0xf
	s_nop 0
	v_add_f32_dpp v38, v38, v38 quad_perm:[2,3,0,1] row_mask:0xf bank_mask:0xf
	v_add_f32_dpp v39, v39, v39 quad_perm:[2,3,0,1] row_mask:0xf bank_mask:0xf
	s_nop 0
	v_add_f32_dpp v38, v38, v38 row_half_mirror row_mask:0xf bank_mask:0xf
	v_add_f32_dpp v39, v39, v39 row_half_mirror row_mask:0xf bank_mask:0xf
	s_nop 0
	v_add_f32_dpp v38, v38, v38 row_mirror row_mask:0xf bank_mask:0xf
	v_add_f32_dpp v39, v39, v39 row_mirror row_mask:0xf bank_mask:0xf
	s_nop 0
	v_mov_b32_e32 v52, v38
	v_mov_b32_e32 v53, v39
	s_nop 0
	v_permlane16_swap_b32_e32 v38, v52
	v_permlane16_swap_b32_e32 v39, v53
	v_add_f32_e32 v38, v38, v52
	v_add_f32_e32 v39, v39, v53
	s_nop 0
	v_pk_fma_f32 v[38:39], v[38:39], s[46:47], v[34:35] op_sel_hi:[1,0,0]
	v_or_b32_e32 v52, 16, v170
	v_mul_f32_e32 v32, 0x4b800000, v39
	v_cmp_gt_f32_e64 s[8:9], s34, v39
	v_cmp_gt_f32_e32 vcc, s34, v38
	v_mov_b32_e32 v53, v171
	v_cndmask_b32_e64 v32, v39, v32, s[8:9]
	v_rsq_f32_e32 v32, v32
	v_lshlrev_b64 v[52:53], 11, v[52:53]
	v_lshl_add_u64 v[52:53], v[172:173], 0, v[52:53]
	v_mul_f32_e32 v39, 0x45800000, v32
	v_cndmask_b32_e64 v32, v32, v39, s[8:9]
	v_mul_f32_e32 v36, v32, v36
	v_mul_f32_e32 v36, v36, v167
	v_bfe_u32 v39, v36, 16, 1
	v_add3_u32 v36, v36, v39, s40
	global_store_short_d16_hi v[54:55], v36, off
	v_mul_f32_e32 v36, v32, v37
	v_mul_f32_e32 v36, v36, v169
	v_bfe_u32 v37, v36, 16, 1
	v_add3_u32 v36, v36, v37, s40
	global_store_short_d16_hi v[54:55], v36, off offset:64
	v_mul_f32_e32 v36, v32, v50
	v_mul_f32_e32 v36, v36, v175
	v_bfe_u32 v37, v36, 16, 1
	v_mul_f32_e32 v32, v32, v51
	v_add3_u32 v36, v36, v37, s40
	v_mul_f32_e32 v32, v32, v177
	global_store_short_d16_hi v[54:55], v36, off offset:128
	v_bfe_u32 v36, v32, 16, 1
	v_add3_u32 v32, v32, v36, s40
	global_store_short_d16_hi v[54:55], v32, off offset:192
	v_mul_f32_e32 v32, 0x4b800000, v38
	v_cndmask_b32_e32 v32, v38, v32, vcc
	v_rsq_f32_e32 v32, v32
	v_mov_b32_e32 v37, v171
	v_mov_b32_e32 v50, v122
	v_mov_b32_e32 v51, v126
	v_mul_f32_e32 v36, 0x45800000, v32
	v_cndmask_b32_e32 v32, v32, v36, vcc
	v_mul_f32_e32 v38, v32, v66
	v_or_b32_e32 v36, 11, v170
	v_mul_f32_e32 v38, v38, v167
	v_lshlrev_b64 v[36:37], 11, v[36:37]
	v_bfe_u32 v39, v38, 16, 1
	v_lshl_add_u64 v[36:37], v[172:173], 0, v[36:37]
	v_add3_u32 v38, v38, v39, s40
	global_store_short_d16_hi v[36:37], v38, off
	v_mul_f32_e32 v38, v32, v67
	v_mul_f32_e32 v38, v38, v169
	v_bfe_u32 v39, v38, 16, 1
	v_add3_u32 v38, v38, v39, s40
	global_store_short_d16_hi v[36:37], v38, off offset:64
	v_mul_f32_e32 v38, v32, v40
	v_mul_f32_e32 v38, v38, v175
	v_bfe_u32 v39, v38, 16, 1
	v_mul_f32_e32 v32, v32, v41
	v_add3_u32 v38, v38, v39, s40
	v_mul_f32_e32 v32, v32, v177
	global_store_short_d16_hi v[36:37], v38, off offset:128
	v_bfe_u32 v38, v32, 16, 1
	v_add3_u32 v32, v32, v38, s40
	global_store_short_d16_hi v[36:37], v32, off offset:192
	v_mov_b32_e32 v36, v90
	v_mov_b32_e32 v37, v74
	v_mov_b32_e32 v74, v91
	v_pk_mul_f32 v[36:37], v[164:165], v[36:37]
	v_mov_b32_e32 v38, v114
	v_mov_b32_e32 v39, v118
	v_mov_b32_e32 v40, v58
	v_mov_b32_e32 v41, v42
	v_pk_mul_f32 v[54:55], v[164:165], v[74:75]
	v_mov_b32_e32 v118, v115
	v_mov_b32_e32 v42, v59
	v_pk_fma_f32 v[36:37], v[182:183], v[36:37], v[38:39] op_sel_hi:[0,1,1] neg_lo:[1,0,0] neg_hi:[1,0,0]
	v_pk_mul_f32 v[40:41], v[164:165], v[40:41]
	v_pk_fma_f32 v[54:55], v[184:185], v[54:55], v[118:119] op_sel_hi:[0,1,1] neg_lo:[1,0,0] neg_hi:[1,0,0]
; __device__ __forceinline__ unsigned f2bf(float f) { unsigned u = __builtin_bit_cast(unsigned, f); return (u + 0x7fffu + ((u >> 16) & 1u)) >> 16; }
; __device__ __forceinline__ int crow(int r, int hi) { return (r & 3) + 8 * (r >> 2) + 4 * hi; }
; __global__ void __launch_bounds__(NWAVES * 64, 2) fwd_kernel(Args args) {
;     ...
;                 for (int r = 0; r < 16; ++r) {
;                     float v[4], sq = 0.f;
; #pragma unroll
;                     for (int db = 0; db < 4; ++db) { v[db] = ((const float*)scrO)[db * 16 + r] - lam * o[db][r] * rl[r]; sq += v[db] * v[db]; }
;                     sq += __shfl_xor(sq, 1); sq += __shfl_xor(sq, 2); sq += __shfl_xor(sq, 4); sq += __shfl_xor(sq, 8); sq += __shfl_xor(sq, 16);
;                     const float rs = rsqrtf(sq * (1.0f / 128.0f) + 1e-6f);
;                     bf16* orow = AO + (row0 + att::crow(r, hi)) * 1024 + h * 128 + r32;
; #pragma unroll
;                     for (int db = 0; db < 4; ++db) orow[32 * db] = (bf16)f2bf(v[db] * rs * g4[db]);
	v_pk_mul_f32 v[42:43], v[164:165], v[42:43]
	v_mov_b32_e32 v126, v123
	v_pk_mul_f32 v[38:39], v[36:37], v[36:37]
	v_pk_fma_f32 v[40:41], v[182:183], v[40:41], v[50:51] op_sel_hi:[0,1,1] neg_lo:[1,0,0] neg_hi:[1,0,0]
	v_pk_mul_f32 v[56:57], v[54:55], v[54:55]
	v_pk_fma_f32 v[42:43], v[184:185], v[42:43], v[126:127] op_sel_hi:[0,1,1] neg_lo:[1,0,0] neg_hi:[1,0,0]
	v_pk_mul_f32 v[50:51], v[40:41], v[40:41]
	v_pk_mul_f32 v[58:59], v[42:43], v[42:43]
	v_mov_b32_e32 v66, v56
	v_mov_b32_e32 v67, v38
	v_mov_b32_e32 v38, v57
	v_pk_add_f32 v[38:39], v[66:67], v[38:39]
	v_mov_b32_e32 v56, v58
	v_mov_b32_e32 v57, v50
	v_pk_add_f32 v[38:39], v[38:39], v[56:57]
	v_mov_b32_e32 v50, v59
	v_pk_add_f32 v[38:39], v[38:39], v[50:51]
	s_nop 1
	v_add_f32_dpp v38, v38, v38 quad_perm:[1,0,3,2] row_mask:0xf bank_mask:0xf
	v_add_f32_dpp v39, v39, v39 quad_perm:[1,0,3,2] row_mask:0xf bank_mask:0xf
	s_nop 0
	v_add_f32_dpp v38, v38, v38 quad_perm:[2,3,0,1] row_mask:0xf bank_mask:0xf
	v_add_f32_dpp v39, v39, v39 quad_perm:[2,3,0,1] row_mask:0xf bank_mask:0xf
	s_nop 0
	v_add_f32_dpp v38, v38, v38 row_half_mirror row_mask:0xf bank_mask:0xf
	v_add_f32_dpp v39, v39, v39 row_half_mirror row_mask:0xf bank_mask:0xf
	s_nop 0
	v_add_f32_dpp v38, v38, v38 row_mirror row_mask:0xf bank_mask:0xf
	v_add_f32_dpp v39, v39, v39 row_mirror row_mask:0xf bank_mask:0xf
	s_nop 0
	v_mov_b32_e32 v50, v38
	v_mov_b32_e32 v51, v39
	s_nop 0
	v_permlane16_swap_b32_e32 v38, v50
	v_permlane16_swap_b32_e32 v39, v51
	v_add_f32_e32 v38, v38, v50
	v_add_f32_e32 v39, v39, v51
	s_nop 0
	v_pk_fma_f32 v[38:39], v[38:39], s[46:47], v[34:35] op_sel_hi:[1,0,0]
	v_or_b32_e32 v50, 18, v170
	v_mul_f32_e32 v32, 0x4b800000, v39
	v_cmp_gt_f32_e64 s[8:9], s34, v39
	v_cmp_gt_f32_e32 vcc, s34, v38
	v_mov_b32_e32 v51, v171
	v_cndmask_b32_e64 v32, v39, v32, s[8:9]
	v_rsq_f32_e32 v32, v32
	v_lshlrev_b64 v[50:51], 11, v[50:51]
	v_lshl_add_u64 v[50:51], v[172:173], 0, v[50:51]
	v_mul_f32_e32 v39, 0x45800000, v32
	v_cndmask_b32_e64 v32, v32, v39, s[8:9]
	v_mul_f32_e32 v36, v32, v36
	v_mul_f32_e32 v36, v36, v167
	v_bfe_u32 v39, v36, 16, 1
	v_add3_u32 v36, v36, v39, s40
	global_store_short_d16_hi v[52:53], v36, off
	v_mul_f32_e32 v36, v32, v37
	v_mul_f32_e32 v36, v36, v169
	v_bfe_u32 v37, v36, 16, 1
	v_add3_u32 v36, v36, v37, s40
	global_store_short_d16_hi v[52:53], v36, off offset:64
	v_mul_f32_e32 v36, v32, v40
	v_mul_f32_e32 v36, v36, v175
	v_bfe_u32 v37, v36, 16, 1
	v_mul_f32_e32 v32, v32, v41
	v_add3_u32 v36, v36, v37, s40
	v_mul_f32_e32 v32, v32, v177
	global_store_short_d16_hi v[52:53], v36, off offset:128
	v_bfe_u32 v36, v32, 16, 1
	v_add3_u32 v32, v32, v36, s40
	global_store_short_d16_hi v[52:53], v32, off offset:192
	v_mul_f32_e32 v32, 0x4b800000, v38
	v_cndmask_b32_e32 v32, v38, v32, vcc
	v_rsq_f32_e32 v32, v32
	v_mov_b32_e32 v37, v171
	v_mov_b32_e32 v40, v60
	v_mov_b32_e32 v41, v44
	v_mul_f32_e32 v36, 0x45800000, v32
	v_cndmask_b32_e32 v32, v32, v36, vcc
	v_mul_f32_e32 v38, v32, v54
	v_or_b32_e32 v36, 17, v170
	v_mul_f32_e32 v38, v38, v167
	v_lshlrev_b64 v[36:37], 11, v[36:37]
	v_bfe_u32 v39, v38, 16, 1
	v_lshl_add_u64 v[36:37], v[172:173], 0, v[36:37]
	v_add3_u32 v38, v38, v39, s40
	global_store_short_d16_hi v[36:37], v38, off
	v_mul_f32_e32 v38, v32, v55
	v_mul_f32_e32 v38, v38, v169
	v_bfe_u32 v39, v38, 16, 1
	v_add3_u32 v38, v38, v39, s40
	global_store_short_d16_hi v[36:37], v38, off offset:64
	v_mul_f32_e32 v38, v32, v42
	v_mul_f32_e32 v38, v38, v175
	v_bfe_u32 v39, v38, 16, 1
	v_mul_f32_e32 v32, v32, v43
	v_add3_u32 v38, v38, v39, s40
	v_mul_f32_e32 v32, v32, v177
	global_store_short_d16_hi v[36:37], v38, off offset:128
	v_bfe_u32 v38, v32, 16, 1
	v_add3_u32 v32, v32, v38, s40
	global_store_short_d16_hi v[36:37], v32, off offset:192
	v_mov_b32_e32 v36, v92
	v_mov_b32_e32 v37, v76
	v_mov_b32_e32 v76, v93
	v_pk_mul_f32 v[36:37], v[164:165], v[36:37]
	v_mov_b32_e32 v38, v116
	v_mov_b32_e32 v39, v120
	v_pk_mul_f32 v[52:53], v[164:165], v[76:77]
	v_mov_b32_e32 v120, v117
	v_mov_b32_e32 v44, v61
	v_pk_fma_f32 v[36:37], v[180:181], v[36:37], v[38:39] op_sel_hi:[0,1,1] neg_lo:[1,0,0] neg_hi:[1,0,0]
	v_pk_mul_f32 v[40:41], v[164:165], v[40:41]
	v_mov_b32_e32 v42, v124
	v_mov_b32_e32 v43, v128
	v_pk_fma_f32 v[52:53], v[178:179], v[52:53], v[120:121] op_sel_hi:[0,1,1] neg_lo:[1,0,0] neg_hi:[1,0,0]
	v_pk_mul_f32 v[44:45], v[164:165], v[44:45]
	v_mov_b32_e32 v128, v125
	v_pk_mul_f32 v[38:39], v[36:37], v[36:37]
	v_pk_fma_f32 v[40:41], v[180:181], v[40:41], v[42:43] op_sel_hi:[0,1,1] neg_lo:[1,0,0] neg_hi:[1,0,0]
	v_pk_mul_f32 v[54:55], v[52:53], v[52:53]
	v_pk_fma_f32 v[44:45], v[178:179], v[44:45], v[128:129] op_sel_hi:[0,1,1] neg_lo:[1,0,0] neg_hi:[1,0,0]
	v_pk_mul_f32 v[42:43], v[40:41], v[40:41]
	v_pk_mul_f32 v[56:57], v[44:45], v[44:45]
	v_mov_b32_e32 v58, v54
	v_mov_b32_e32 v59, v38
	v_mov_b32_e32 v38, v55
	v_pk_add_f32 v[38:39], v[58:59], v[38:39]
	v_mov_b32_e32 v54, v56
	v_mov_b32_e32 v55, v42
	v_pk_add_f32 v[38:39], v[38:39], v[54:55]
	v_mov_b32_e32 v42, v57
	v_pk_add_f32 v[38:39], v[38:39], v[42:43]
	s_nop 1
	v_add_f32_dpp v38, v38, v38 quad_perm:[1,0,3,2] row_mask:0xf bank_mask:0xf
	v_add_f32_dpp v39, v39, v39 quad_perm:[1,0,3,2] row_mask:0xf bank_mask:0xf
	s_nop 0
	v_add_f32_dpp v38, v38, v38 quad_perm:[2,3,0,1] row_mask:0xf bank_mask:0xf
	v_add_f32_dpp v39, v39, v39 quad_perm:[2,3,0,1] row_mask:0xf bank_mask:0xf
	s_nop 0
	v_add_f32_dpp v38, v38, v38 row_half_mirror row_mask:0xf bank_mask:0xf
	v_add_f32_dpp v39, v39, v39 row_half_mirror row_mask:0xf bank_mask:0xf
	s_nop 0
	v_add_f32_dpp v38, v38, v38 row_mirror row_mask:0xf bank_mask:0xf
	v_add_f32_dpp v39, v39, v39 row_mirror row_mask:0xf bank_mask:0xf
; __device__ __forceinline__ unsigned f2bf(float f) { unsigned u = __builtin_bit_cast(unsigned, f); return (u + 0x7fffu + ((u >> 16) & 1u)) >> 16; }
; __device__ __forceinline__ int crow(int r, int hi) { return (r & 3) + 8 * (r >> 2) + 4 * hi; }
; __global__ void __launch_bounds__(NWAVES * 64, 2) fwd_kernel(Args args) {
;     ...
;                 for (int r = 0; r < 16; ++r) {
;                     float v[4], sq = 0.f;
; #pragma unroll
;                     for (int db = 0; db < 4; ++db) { v[db] = ((const float*)scrO)[db * 16 + r] - lam * o[db][r] * rl[r]; sq += v[db] * v[db]; }
;                     sq += __shfl_xor(sq, 1); sq += __shfl_xor(sq, 2); sq += __shfl_xor(sq, 4); sq += __shfl_xor(sq, 8); sq += __shfl_xor(sq, 16);
;                     const float rs = rsqrtf(sq * (1.0f / 128.0f) + 1e-6f);
;                     bf16* orow = AO + (row0 + att::crow(r, hi)) * 1024 + h * 128 + r32;
; #pragma unroll
;                     for (int db = 0; db < 4; ++db) orow[32 * db] = (bf16)f2bf(v[db] * rs * g4[db]);
	s_nop 0
	v_mov_b32_e32 v42, v38
	v_mov_b32_e32 v43, v39
	s_nop 0
	v_permlane16_swap_b32_e32 v38, v42
	v_permlane16_swap_b32_e32 v39, v43
	v_add_f32_e32 v38, v38, v42
	v_add_f32_e32 v39, v39, v43
	s_nop 0
	v_pk_fma_f32 v[38:39], v[38:39], s[46:47], v[34:35] op_sel_hi:[1,0,0]
	v_mov_b32_e32 v42, v106
	v_mul_f32_e32 v32, 0x4b800000, v39
	v_cmp_gt_f32_e64 s[8:9], s34, v39
	v_cmp_gt_f32_e32 vcc, s34, v38
	v_mov_b32_e32 v43, v110
	v_cndmask_b32_e64 v32, v39, v32, s[8:9]
	v_rsq_f32_e32 v32, v32
	v_mov_b32_e32 v110, v107
	v_mul_f32_e32 v39, 0x45800000, v32
	v_cndmask_b32_e64 v32, v32, v39, s[8:9]
	v_mul_f32_e32 v36, v32, v36
	v_mul_f32_e32 v36, v36, v167
	v_bfe_u32 v39, v36, 16, 1
	v_add3_u32 v36, v36, v39, s40
	global_store_short_d16_hi v[50:51], v36, off
	v_mul_f32_e32 v36, v32, v37
	v_mul_f32_e32 v36, v36, v169
	v_bfe_u32 v37, v36, 16, 1
	v_add3_u32 v36, v36, v37, s40
	global_store_short_d16_hi v[50:51], v36, off offset:64
	v_mul_f32_e32 v36, v32, v40
	v_mul_f32_e32 v36, v36, v175
	v_bfe_u32 v37, v36, 16, 1
	v_mul_f32_e32 v32, v32, v41
	v_add3_u32 v36, v36, v37, s40
	v_mul_f32_e32 v32, v32, v177
	global_store_short_d16_hi v[50:51], v36, off offset:128
	v_bfe_u32 v36, v32, 16, 1
	v_add3_u32 v32, v32, v36, s40
	global_store_short_d16_hi v[50:51], v32, off offset:192
	v_mul_f32_e32 v32, 0x4b800000, v38
	v_cndmask_b32_e32 v32, v38, v32, vcc
	v_rsq_f32_e32 v32, v32
	v_mov_b32_e32 v37, v171
	v_mov_b32_e32 v40, v62
	v_mov_b32_e32 v41, v46
	v_mul_f32_e32 v36, 0x45800000, v32
	v_cndmask_b32_e32 v32, v32, v36, vcc
	v_mul_f32_e32 v38, v32, v52
	v_or_b32_e32 v36, 19, v170
	v_mul_f32_e32 v38, v38, v167
	v_lshlrev_b64 v[36:37], 11, v[36:37]
	v_bfe_u32 v39, v38, 16, 1
	v_lshl_add_u64 v[36:37], v[172:173], 0, v[36:37]
	v_add3_u32 v38, v38, v39, s40
	global_store_short_d16_hi v[36:37], v38, off
	v_mul_f32_e32 v38, v32, v53
	v_mul_f32_e32 v38, v38, v169
	v_bfe_u32 v39, v38, 16, 1
	v_add3_u32 v38, v38, v39, s40
	global_store_short_d16_hi v[36:37], v38, off offset:64
	v_mul_f32_e32 v38, v32, v44
	v_mul_f32_e32 v38, v38, v175
	v_bfe_u32 v39, v38, 16, 1
	v_mul_f32_e32 v32, v32, v45
	v_add3_u32 v38, v38, v39, s40
	v_mul_f32_e32 v32, v32, v177
	global_store_short_d16_hi v[36:37], v38, off offset:128
	v_bfe_u32 v38, v32, 16, 1
	v_add3_u32 v32, v32, v38, s40
	global_store_short_d16_hi v[36:37], v32, off offset:192
	v_mov_b32_e32 v36, v94
	v_mov_b32_e32 v37, v78
	v_mov_b32_e32 v78, v95
	v_pk_mul_f32 v[36:37], v[164:165], v[36:37]
	v_mov_b32_e32 v38, v98
	v_mov_b32_e32 v39, v102
	v_pk_mul_f32 v[50:51], v[164:165], v[78:79]
	v_mov_b32_e32 v102, v99
	v_mov_b32_e32 v46, v63
	v_pk_fma_f32 v[36:37], v[176:177], v[36:37], v[38:39] op_sel_hi:[0,1,1] neg_lo:[1,0,0] neg_hi:[1,0,0]
	v_pk_mul_f32 v[40:41], v[164:165], v[40:41]
	v_pk_fma_f32 v[50:51], v[174:175], v[50:51], v[102:103] op_sel_hi:[0,1,1] neg_lo:[1,0,0] neg_hi:[1,0,0]
	v_pk_mul_f32 v[46:47], v[164:165], v[46:47]
	v_pk_mul_f32 v[38:39], v[36:37], v[36:37]
	v_pk_fma_f32 v[40:41], v[176:177], v[40:41], v[42:43] op_sel_hi:[0,1,1] neg_lo:[1,0,0] neg_hi:[1,0,0]
	v_pk_mul_f32 v[52:53], v[50:51], v[50:51]
	v_pk_fma_f32 v[46:47], v[174:175], v[46:47], v[110:111] op_sel_hi:[0,1,1] neg_lo:[1,0,0] neg_hi:[1,0,0]
	v_pk_mul_f32 v[42:43], v[40:41], v[40:41]
	v_pk_mul_f32 v[54:55], v[46:47], v[46:47]
	v_mov_b32_e32 v56, v52
	v_mov_b32_e32 v57, v38
	v_mov_b32_e32 v38, v53
	v_pk_add_f32 v[38:39], v[56:57], v[38:39]
	v_mov_b32_e32 v52, v54
	v_mov_b32_e32 v53, v42
	v_pk_add_f32 v[38:39], v[38:39], v[52:53]
	v_mov_b32_e32 v42, v55
	v_pk_add_f32 v[38:39], v[38:39], v[42:43]
	s_nop 1
	v_add_f32_dpp v38, v38, v38 quad_perm:[1,0,3,2] row_mask:0xf bank_mask:0xf
	v_add_f32_dpp v39, v39, v39 quad_perm:[1,0,3,2] row_mask:0xf bank_mask:0xf
	s_nop 0
	v_add_f32_dpp v38, v38, v38 quad_perm:[2,3,0,1] row_mask:0xf bank_mask:0xf
	v_add_f32_dpp v39, v39, v39 quad_perm:[2,3,0,1] row_mask:0xf bank_mask:0xf
	s_nop 0
	v_add_f32_dpp v38, v38, v38 row_half_mirror row_mask:0xf bank_mask:0xf
	v_add_f32_dpp v39, v39, v39 row_half_mirror row_mask:0xf bank_mask:0xf
	s_nop 0
	v_add_f32_dpp v38, v38, v38 row_mirror row_mask:0xf bank_mask:0xf
	v_add_f32_dpp v39, v39, v39 row_mirror row_mask:0xf bank_mask:0xf
	s_nop 0
	v_mov_b32_e32 v42, v38
	v_mov_b32_e32 v43, v39
	s_nop 0
	v_permlane16_swap_b32_e32 v38, v42
	v_permlane16_swap_b32_e32 v39, v43
	v_add_f32_e32 v38, v38, v42
	v_add_f32_e32 v39, v39, v43
	v_or_b32_e32 v44, 24, v170
	v_mov_b32_e32 v45, v171
	v_lshlrev_b64 v[44:45], 11, v[44:45]
	v_lshl_add_u64 v[44:45], v[172:173], 0, v[44:45]
	s_nop 0
	v_pk_fma_f32 v[38:39], v[38:39], s[46:47], v[34:35] op_sel_hi:[1,0,0]
	v_mov_b32_e32 v42, v108
	v_mul_f32_e32 v32, 0x4b800000, v39
	v_cmp_gt_f32_e64 s[8:9], s34, v39
	v_cmp_gt_f32_e32 vcc, s34, v38
	v_mov_b32_e32 v43, v112
	v_cndmask_b32_e64 v32, v39, v32, s[8:9]
	v_rsq_f32_e32 v32, v32
	v_mov_b32_e32 v112, v109
	v_mul_f32_e32 v39, 0x45800000, v32
	v_cndmask_b32_e64 v32, v32, v39, s[8:9]
	v_mul_f32_e32 v36, v32, v36
	v_mul_f32_e32 v36, v36, v167
	v_bfe_u32 v39, v36, 16, 1
	v_add3_u32 v36, v36, v39, s40
	global_store_short_d16_hi v[44:45], v36, off
	v_mul_f32_e32 v36, v32, v37
	v_mul_f32_e32 v36, v36, v169
	v_bfe_u32 v37, v36, 16, 1
	v_add3_u32 v36, v36, v37, s40
	global_store_short_d16_hi v[44:45], v36, off offset:64
	v_mul_f32_e32 v36, v32, v40
	v_mul_f32_e32 v36, v36, v175
	v_bfe_u32 v37, v36, 16, 1
	v_mul_f32_e32 v32, v32, v41
	v_add3_u32 v36, v36, v37, s40
	v_mul_f32_e32 v32, v32, v177
	global_store_short_d16_hi v[44:45], v36, off offset:128
; __device__ __forceinline__ unsigned f2bf(float f) { unsigned u = __builtin_bit_cast(unsigned, f); return (u + 0x7fffu + ((u >> 16) & 1u)) >> 16; }
; __device__ __forceinline__ int crow(int r, int hi) { return (r & 3) + 8 * (r >> 2) + 4 * hi; }
; __global__ void __launch_bounds__(NWAVES * 64, 2) fwd_kernel(Args args) {
;     ...
;                 for (int r = 0; r < 16; ++r) {
;                     float v[4], sq = 0.f;
; #pragma unroll
;                     for (int db = 0; db < 4; ++db) { v[db] = ((const float*)scrO)[db * 16 + r] - lam * o[db][r] * rl[r]; sq += v[db] * v[db]; }
;                     sq += __shfl_xor(sq, 1); sq += __shfl_xor(sq, 2); sq += __shfl_xor(sq, 4); sq += __shfl_xor(sq, 8); sq += __shfl_xor(sq, 16);
;                     const float rs = rsqrtf(sq * (1.0f / 128.0f) + 1e-6f);
;                     bf16* orow = AO + (row0 + att::crow(r, hi)) * 1024 + h * 128 + r32;
; #pragma unroll
;                     for (int db = 0; db < 4; ++db) orow[32 * db] = (bf16)f2bf(v[db] * rs * g4[db]);
	v_bfe_u32 v36, v32, 16, 1
	v_add3_u32 v32, v32, v36, s40
	global_store_short_d16_hi v[44:45], v32, off offset:192
	v_mul_f32_e32 v32, 0x4b800000, v38
	v_cndmask_b32_e32 v32, v38, v32, vcc
	v_rsq_f32_e32 v32, v32
	v_mov_b32_e32 v37, v171
	v_mov_b32_e32 v40, v64
	v_mov_b32_e32 v41, v48
	v_mul_f32_e32 v36, 0x45800000, v32
	v_cndmask_b32_e32 v32, v32, v36, vcc
	v_mul_f32_e32 v38, v32, v50
	v_or_b32_e32 v36, 25, v170
	v_mul_f32_e32 v38, v38, v167
	v_lshlrev_b64 v[36:37], 11, v[36:37]
	v_bfe_u32 v39, v38, 16, 1
	v_lshl_add_u64 v[36:37], v[172:173], 0, v[36:37]
	v_add3_u32 v38, v38, v39, s40
	global_store_short_d16_hi v[36:37], v38, off
	v_mul_f32_e32 v38, v32, v51
	v_mul_f32_e32 v38, v38, v169
	v_bfe_u32 v39, v38, 16, 1
	v_add3_u32 v38, v38, v39, s40
	global_store_short_d16_hi v[36:37], v38, off offset:64
	v_mul_f32_e32 v38, v32, v46
	v_mul_f32_e32 v38, v38, v175
	v_bfe_u32 v39, v38, 16, 1
	v_mul_f32_e32 v32, v32, v47
	v_add3_u32 v38, v38, v39, s40
	v_mul_f32_e32 v32, v32, v177
	global_store_short_d16_hi v[36:37], v38, off offset:128
	v_bfe_u32 v38, v32, 16, 1
	v_add3_u32 v32, v32, v38, s40
	global_store_short_d16_hi v[36:37], v32, off offset:192
	v_mov_b32_e32 v36, v96
	v_mov_b32_e32 v37, v80
	v_mov_b32_e32 v80, v97
	v_pk_mul_f32 v[36:37], v[164:165], v[36:37]
	v_mov_b32_e32 v38, v100
	v_mov_b32_e32 v39, v104
	v_pk_mul_f32 v[46:47], v[164:165], v[80:81]
	v_mov_b32_e32 v104, v101
	v_mov_b32_e32 v48, v65
	v_pk_fma_f32 v[36:37], v[168:169], v[36:37], v[38:39] op_sel_hi:[0,1,1] neg_lo:[1,0,0] neg_hi:[1,0,0]
	v_pk_mul_f32 v[40:41], v[164:165], v[40:41]
	v_pk_fma_f32 v[46:47], v[166:167], v[46:47], v[104:105] op_sel_hi:[0,1,1] neg_lo:[1,0,0] neg_hi:[1,0,0]
	v_pk_mul_f32 v[48:49], v[164:165], v[48:49]
	v_pk_mul_f32 v[38:39], v[36:37], v[36:37]
	v_pk_fma_f32 v[40:41], v[168:169], v[40:41], v[42:43] op_sel_hi:[0,1,1] neg_lo:[1,0,0] neg_hi:[1,0,0]
	v_pk_mul_f32 v[50:51], v[46:47], v[46:47]
	v_pk_fma_f32 v[48:49], v[166:167], v[48:49], v[112:113] op_sel_hi:[0,1,1] neg_lo:[1,0,0] neg_hi:[1,0,0]
	v_pk_mul_f32 v[42:43], v[40:41], v[40:41]
	v_pk_mul_f32 v[52:53], v[48:49], v[48:49]
	v_mov_b32_e32 v54, v50
	v_mov_b32_e32 v55, v38
	v_mov_b32_e32 v38, v51
	v_pk_add_f32 v[38:39], v[54:55], v[38:39]
	v_mov_b32_e32 v50, v52
	v_mov_b32_e32 v51, v42
	v_pk_add_f32 v[38:39], v[38:39], v[50:51]
	v_mov_b32_e32 v42, v53
	v_pk_add_f32 v[38:39], v[38:39], v[42:43]
	s_nop 1
	v_add_f32_dpp v38, v38, v38 quad_perm:[1,0,3,2] row_mask:0xf bank_mask:0xf
	v_add_f32_dpp v39, v39, v39 quad_perm:[1,0,3,2] row_mask:0xf bank_mask:0xf
	s_nop 0
	v_add_f32_dpp v38, v38, v38 quad_perm:[2,3,0,1] row_mask:0xf bank_mask:0xf
	v_add_f32_dpp v39, v39, v39 quad_perm:[2,3,0,1] row_mask:0xf bank_mask:0xf
	s_nop 0
	v_add_f32_dpp v38, v38, v38 row_half_mirror row_mask:0xf bank_mask:0xf
	v_add_f32_dpp v39, v39, v39 row_half_mirror row_mask:0xf bank_mask:0xf
	s_nop 0
	v_add_f32_dpp v38, v38, v38 row_mirror row_mask:0xf bank_mask:0xf
	v_add_f32_dpp v39, v39, v39 row_mirror row_mask:0xf bank_mask:0xf
	s_nop 0
	v_mov_b32_e32 v42, v38
	v_mov_b32_e32 v43, v39
	s_nop 0
	v_permlane16_swap_b32_e32 v38, v42
	v_permlane16_swap_b32_e32 v39, v43
	v_add_f32_e32 v38, v38, v42
	v_add_f32_e32 v39, v39, v43
	v_or_b32_e32 v44, 26, v170
	v_mov_b32_e32 v45, v171
	v_lshlrev_b64 v[44:45], 11, v[44:45]
	v_lshl_add_u64 v[44:45], v[172:173], 0, v[44:45]
	v_or_b32_e32 v170, 27, v170
	s_nop 0
	v_pk_fma_f32 v[34:35], v[38:39], s[46:47], v[34:35] op_sel_hi:[1,0,0]
	s_nop 0
	v_mul_f32_e32 v32, 0x4b800000, v35
	v_cmp_gt_f32_e64 s[8:9], s34, v35
	v_cmp_gt_f32_e32 vcc, s34, v34
	s_nop 0
	v_cndmask_b32_e64 v32, v35, v32, s[8:9]
	v_rsq_f32_e32 v32, v32
	s_nop 0
	v_mul_f32_e32 v35, 0x45800000, v32
	v_cndmask_b32_e64 v32, v32, v35, s[8:9]
	v_mul_f32_e32 v35, v32, v36
	v_mul_f32_e32 v35, v35, v167
	v_bfe_u32 v36, v35, 16, 1
	v_add3_u32 v35, v35, v36, s40
	global_store_short_d16_hi v[44:45], v35, off
	v_mul_f32_e32 v35, v32, v37
	v_mul_f32_e32 v35, v35, v169
	v_bfe_u32 v36, v35, 16, 1
	v_add3_u32 v35, v35, v36, s40
	global_store_short_d16_hi v[44:45], v35, off offset:64
	v_mul_f32_e32 v35, v32, v40
	v_mul_f32_e32 v35, v35, v175
	v_bfe_u32 v36, v35, 16, 1
	v_mul_f32_e32 v32, v32, v41
	v_add3_u32 v35, v35, v36, s40
	v_mul_f32_e32 v32, v32, v177
	global_store_short_d16_hi v[44:45], v35, off offset:128
	v_bfe_u32 v35, v32, 16, 1
	v_add3_u32 v32, v32, v35, s40
	global_store_short_d16_hi v[44:45], v32, off offset:192
	v_mul_f32_e32 v32, 0x4b800000, v34
	v_cndmask_b32_e32 v32, v34, v32, vcc
	v_rsq_f32_e32 v32, v32
	s_nop 0
	v_mul_f32_e32 v34, 0x45800000, v32
	v_cndmask_b32_e32 v32, v32, v34, vcc
	v_mul_f32_e32 v36, v32, v46
	v_mul_f32_e32 v36, v36, v167
	v_lshlrev_b64 v[34:35], 11, v[170:171]
	v_bfe_u32 v37, v36, 16, 1
	v_lshl_add_u64 v[34:35], v[172:173], 0, v[34:35]
	v_add3_u32 v36, v36, v37, s40
	global_store_short_d16_hi v[34:35], v36, off
	v_mul_f32_e32 v36, v32, v47
	v_mul_f32_e32 v36, v36, v169
	v_bfe_u32 v37, v36, 16, 1
	v_add3_u32 v36, v36, v37, s40
	global_store_short_d16_hi v[34:35], v36, off offset:64
	v_mul_f32_e32 v36, v32, v48
	v_mul_f32_e32 v36, v36, v175
	v_bfe_u32 v37, v36, 16, 1
	v_mul_f32_e32 v32, v32, v49
	v_add3_u32 v36, v36, v37, s40
	v_mul_f32_e32 v32, v32, v177
	global_store_short_d16_hi v[34:35], v36, off offset:128
	v_bfe_u32 v36, v32, 16, 1
	v_add3_u32 v32, v32, v36, s40
	s_and_b64 vcc, exec, s[64:65]
	global_store_short_d16_hi v[34:35], v32, off offset:192
	s_cbranch_vccnz .LBB0_606
